# k21
# baseline (speedup 1.0000x reference)
; #define BAR __builtin_amdgcn_s_barrier()
; template <int EPI>
; __device__ __forceinline__ void gemm_phase(const GemmDesc d, u16* shm, unsigned sx, unsigned srank, unsigned snloc) {
;     ...
;       if (wr == 0) BAR;
;       int t2 = threadIdx.x; asm volatile("" : "+v"(t2));
;       const int wid2 = t2 >> 6, lane2 = t2 & 63, wr2 = wid2 >> 2, wc2 = wid2 & 3, fr2 = lane2 & 15, fq2 = lane2 >> 4;
;       float ssn = 0.f;
;       if constexpr (NEED_R) {
;         if (has_next && t2 < 256) ssn = SS_ROW(d.ss + (size_t)R_ROW(pmn, pnn, t2) * 16);
;       }
;       float* stg = (float*)((char*)shm + GEMM_LDS + 2048 + wid2 * 2304);
;     ...
;         const int rl16 = lane2 >> 2, c8 = (lane2 & 3) * 8;
;         f32x4 cs[2][2], cb[2][2];
; #pragma unroll
;         for (int bj = 0; bj < 2; ++bj)
; #pragma unroll
;           for (int hh = 0; hh < 2; ++hh) {
;             const int lcol = bj * 128 + wc2 * 32 + c8 + hh * 4;
;             cs[bj][hh] = f32x4{1.f, 1.f, 1.f, 1.f}; cb[bj][hh] = f32x4{0.f, 0.f, 0.f, 0.f};
;             if constexpr (EPI == E_SEQDFT) { cs[bj][hh] = f32x4{1.f / 1024.f, 1.f / 1024.f, 1.f / 1024.f, 1.f / 1024.f}; cb[bj][hh] = *(const f32x4*)(d.bias + (size_t)z * DM + bcol + lcol); }
;             if constexpr (EPI == E_RESID) {
;               if (d.bias) cb[bj][hh] = *(const f32x4*)(d.bias + bcol + lcol);
;               if (d.scale) cs[bj][hh] = *(const f32x4*)(d.scale + bcol + lcol);
;               cs[bj][hh] = cs[bj][hh] * d.alpha;
;             }
;           }
;         u16* outp = nullptr; int ldo = 0;
;         if constexpr (EPI == E_QKV) { outp = (u16*)((char*)(d.outb + (size_t)brow * DQKV + bcol) + (long)(pm >> 4) * d.o_bskip); ldo = DQKV; }
;         if constexpr (EPI == E_SEQDFT) { outp = d.outb + ((size_t)z * SEQ + brow) * DM + bcol; ldo = DM; }
;         const size_t xbase = (size_t)(brow + wr2 * 64 + rl16) * DM + bcol + wc2 * 32 + c8;
;         u32x4 xi = {0u, 0u, 0u, 0u};
;         if constexpr (EPI == E_RESID) xi = *(const u32x4*)(d.xb + xbase);
; #pragma unroll
;         for (int ai = 0; ai < 2; ++ai)
; #pragma unroll
;           for (int m = 0; m < 4; ++m) {
;             float ps = 0.f;
;             const int lrow = ai * 128 + wr2 * 64 + m * 16 + rl16;
; #pragma unroll
;             for (int bj = 0; bj < 2; ++bj) {
; #pragma unroll
;               for (int n = 0; n < 2; ++n)
; #pragma unroll
.LBB0_1538:
	v_lshrrev_b32_e32 v210, 6, v182
	v_and_b32_e32 v211, 3, v182
	v_bfe_u32 v212, v182, 2, 4
	v_lshrrev_b32_e32 v213, 2, v182
	v_and_b32_e32 v213, 12, v213
	v_and_b32_e32 v148, 15, v182
	v_lshlrev_b32_e32 v148, 2, v148
	v_and_b32_e32 v149, 3, v210
	v_mul_u32_u24_e32 v150, 0x900, v210
	v_add_u32_e32 v150, s83, v150
	v_mul_u32_u24_e32 v152, 0x90, v213
	v_add3_u32 v144, v150, v148, v152
	v_mul_u32_u24_e32 v152, 0x90, v212
	v_lshlrev_b32_e32 v153, 5, v211
	v_add3_u32 v145, v150, v152, v153
	v_lshrrev_b32_e32 v151, 2, v182
	v_and_b32_e32 v151, 0xffffffc0, v151
	v_or_b32_e32 v151, v151, v212
	v_lshlrev_b32_e32 v152, 11, v151
	v_lshlrev_b32_e32 v153, 6, v149
	v_lshlrev_b32_e32 v146, 4, v211
	v_add3_u32 v146, v152, v153, v146
	v_lshlrev_b32_e32 v152, 6, v151
	v_lshlrev_b32_e32 v153, 2, v149
	v_add_u32_e32 v147, v152, v153
	v_cmp_eq_u32_e64 s[10:11], 0, v211
	v_xor_b32_e32 v154, 1, v185
	v_lshlrev_b32_e32 v154, 2, v154
	v_xor_b32_e32 v155, 2, v185
	v_lshlrev_b32_e32 v155, 2, v155
	s_lshl_b32 s0, s88, 19
	s_lshl_b32 s1, s85, 9
	s_add_u32 s0, s0, s1
	s_add_u32 s46, s2, s0
	s_addc_u32 s47, s3, 0
	s_lshl_b32 s0, s88, 14
	s_lshl_b32 s1, s85, 4
	s_add_u32 s0, s0, s1
	s_add_u32 s42, s67, s0
	s_addc_u32 s43, s69, 0
	s_add_u32 s34, s46, 0x0
	s_addc_u32 s35, s47, 0
	global_load_dwordx4 v[158:161], v146, s[34:35]
	global_load_dwordx4 v[162:165], v146, s[34:35] offset:256
	s_add_u32 s34, s46, 0x8000
	s_addc_u32 s35, s47, 0
	global_load_dwordx4 v[166:169], v146, s[34:35]
	global_load_dwordx4 v[170:173], v146, s[34:35] offset:256
	s_add_u32 s34, s46, 0x10000
	s_addc_u32 s35, s47, 0
	global_load_dwordx4 v[178:181], v146, s[34:35]
	global_load_dwordx4 v[190:193], v146, s[34:35] offset:256
	s_and_b64 vcc, exec, s[8:9]
	s_cbranch_vccz .Ldn_ra_skip
	s_barrier
.Ldn_ra_skip:
	ds_write2_b32 v144, v124, v120 offset1:16
	ds_write2_b32 v144, v125, v121 offset0:36 offset1:52
	ds_write2_b32 v144, v126, v122 offset0:72 offset1:88
	ds_write2_b32 v144, v127, v123 offset0:108 offset1:124
	ds_read_b128 v[194:197], v145
	ds_read_b128 v[198:201], v145 offset:16
	ds_write2_b32 v144, v116, v112 offset1:16
	ds_write2_b32 v144, v117, v113 offset0:36 offset1:52
	ds_write2_b32 v144, v118, v114 offset0:72 offset1:88
	ds_write2_b32 v144, v119, v115 offset0:108 offset1:124
	ds_read_b128 v[202:205], v145
	ds_read_b128 v[206:209], v145 offset:16
	s_waitcnt lgkmcnt(6)
	s_waitcnt vmcnt(5)
	v_lshlrev_b32_e32 v210, 16, v158
	v_and_b32_e32 v211, 0xffff0000, v158
	v_lshlrev_b32_e32 v212, 16, v159
	v_and_b32_e32 v213, 0xffff0000, v159
	v_lshlrev_b32_e32 v148, 16, v160
	v_and_b32_e32 v149, 0xffff0000, v160
	v_lshlrev_b32_e32 v150, 16, v161
	v_and_b32_e32 v151, 0xffff0000, v161
	s_add_u32 s34, s46, 0x18000
	s_addc_u32 s35, s47, 0
	global_load_dwordx4 v[158:161], v146, s[34:35]
	v_pk_fma_f32 v[210:211], v[194:195], 0.5, v[210:211] op_sel_hi:[1,0,1]
	v_pk_fma_f32 v[212:213], v[196:197], 0.5, v[212:213] op_sel_hi:[1,0,1]
	v_pk_fma_f32 v[148:149], v[198:199], 0.5, v[148:149] op_sel_hi:[1,0,1]
	v_pk_fma_f32 v[150:151], v[200:201], 0.5, v[150:151] op_sel_hi:[1,0,1]
	v_cvt_pk_bf16_f32 v194, v210, v211
	v_cvt_pk_bf16_f32 v195, v212, v213
	v_cvt_pk_bf16_f32 v196, v148, v149
	v_cvt_pk_bf16_f32 v197, v150, v151
	s_add_u32 s22, s46, 0x0
	s_addc_u32 s23, s47, 0
	global_store_dwordx4 v146, v[194:197], s[22:23]
	v_pk_mul_f32 v[152:153], v[148:149], v[148:149]
	v_pk_mul_f32 v[156:157], v[150:151], v[150:151]
	v_pk_fma_f32 v[152:153], v[210:211], v[210:211], v[152:153]
	v_pk_fma_f32 v[156:157], v[212:213], v[212:213], v[156:157]
	v_add_f32_e32 v152, v152, v153
	v_add_f32_e32 v153, v156, v157
	v_add_f32_e32 v128, v152, v153
	ds_write2_b32 v144, v108, v104 offset1:16
	ds_write2_b32 v144, v109, v105 offset0:36 offset1:52
	ds_write2_b32 v144, v110, v106 offset0:72 offset1:88
	ds_write2_b32 v144, v111, v107 offset0:108 offset1:124
	ds_read_b128 v[194:197], v145
	ds_read_b128 v[198:201], v145 offset:16
	s_waitcnt lgkmcnt(6)
	s_waitcnt vmcnt(6)
	v_lshlrev_b32_e32 v210, 16, v162
	v_and_b32_e32 v211, 0xffff0000, v162
	v_lshlrev_b32_e32 v212, 16, v163
	v_and_b32_e32 v213, 0xffff0000, v163
	v_lshlrev_b32_e32 v148, 16, v164
	v_and_b32_e32 v149, 0xffff0000, v164
	v_lshlrev_b32_e32 v150, 16, v165
	v_and_b32_e32 v151, 0xffff0000, v165
	global_load_dwordx4 v[162:165], v146, s[34:35] offset:256
	v_pk_fma_f32 v[210:211], v[202:203], 0.5, v[210:211] op_sel_hi:[1,0,1]
	v_pk_fma_f32 v[212:213], v[204:205], 0.5, v[212:213] op_sel_hi:[1,0,1]
	v_pk_fma_f32 v[148:149], v[206:207], 0.5, v[148:149] op_sel_hi:[1,0,1]
	v_pk_fma_f32 v[150:151], v[208:209], 0.5, v[150:151] op_sel_hi:[1,0,1]
	v_cvt_pk_bf16_f32 v202, v210, v211
	v_cvt_pk_bf16_f32 v203, v212, v213
	v_cvt_pk_bf16_f32 v204, v148, v149
	v_cvt_pk_bf16_f32 v205, v150, v151
	global_store_dwordx4 v146, v[202:205], s[22:23] offset:256
	v_pk_mul_f32 v[152:153], v[148:149], v[148:149]
	v_pk_mul_f32 v[156:157], v[150:151], v[150:151]
	v_pk_fma_f32 v[152:153], v[210:211], v[210:211], v[152:153]
	v_pk_fma_f32 v[156:157], v[212:213], v[212:213], v[156:157]
	v_add_f32_e32 v152, v152, v153
	v_add_f32_e32 v153, v156, v157
	v_add_f32_e32 v152, v152, v153
	v_add_f32_e32 v129, v128, v152
	ds_bpermute_b32 v130, v154, v129
	ds_write2_b32 v144, v100, v96 offset1:16
	ds_write2_b32 v144, v101, v97 offset0:36 offset1:52
	ds_write2_b32 v144, v102, v98 offset0:72 offset1:88
	ds_write2_b32 v144, v103, v99 offset0:108 offset1:124
	ds_read_b128 v[202:205], v145
	ds_read_b128 v[206:209], v145 offset:16
	s_waitcnt lgkmcnt(6)
	v_add_f32_e32 v131, v129, v130
	ds_bpermute_b32 v132, v155, v131
	s_waitcnt lgkmcnt(8)
	s_waitcnt vmcnt(7)
; template <int EPI>
; __device__ __forceinline__ void gemm_phase(const GemmDesc d, u16* shm, unsigned sx, unsigned srank, unsigned snloc) {
;     ...
;             for (int bj = 0; bj < 2; ++bj) {
; #pragma unroll
;               for (int n = 0; n < 2; ++n)
; #pragma unroll
;                 for (int j = 0; j < 4; ++j) stg[(fq2 * 4 + j) * 36 + n * 16 + fr2] = acc[ai][bj][m][n][j];
;               u32x4 xc = xi;
;               if constexpr (EPI == E_RESID) {
;                 const int rnd = (ai * 4 + m) * 2 + bj;
;                 if (rnd < 15) {
;                   const int rn = rnd + 1, an = rn >> 3, mn = (rn >> 1) & 3, bn = rn & 1;
;                   xi = *(const u32x4*)(d.xb + xbase + (size_t)(an * 128 + mn * 16) * DM + bn * 128);
;                 }
;               }
;               f32x4 v0 = *(const f32x4*)&stg[rl16 * 36 + c8], v1 = *(const f32x4*)&stg[rl16 * 36 + c8 + 4];
;               if constexpr (EPI == E_RESID) {
;                 const size_t idx = xbase + (size_t)(ai * 128 + m * 16) * DM + bj * 128;
;                 const f32x4 xo0 = {__uint_as_float(xc[0] << 16), __uint_as_float(xc[0] & 0xffff0000u), __uint_as_float(xc[1] << 16), __uint_as_float(xc[1] & 0xffff0000u)};
;                 const f32x4 xo1 = {__uint_as_float(xc[2] << 16), __uint_as_float(xc[2] & 0xffff0000u), __uint_as_float(xc[3] << 16), __uint_as_float(xc[3] & 0xffff0000u)};
;                 const f32x4 xn0 = xo0 + (v0 + cb[bj][0]) * cs[bj][0], xn1 = xo1 + (v1 + cb[bj][1]) * cs[bj][1];
;                 u32x4 w = {pack2(xn0[0], xn0[1]), pack2(xn0[2], xn0[3]), pack2(xn1[0], xn1[1]), pack2(xn1[2], xn1[3])};
;                 *(u32x4*)(d.xb + idx) = w;
;                 const f32x4 sq = xn0 * xn0 + xn1 * xn1;
;                 ps += (sq[0] + sq[1]) + (sq[2] + sq[3]);
;               } else {
;                 if constexpr (EPI == E_QKV) { const float r = lr[lrow]; v0 = v0 * r; v1 = v1 * r; }
;                 else if constexpr (EPI == E_SEQDFT) { const float sg = (rl16 & 1) ? -1.f : 1.f; v0 = (v0 + cb[bj][0] * sg) * cs[bj][0]; v1 = (v1 + cb[bj][1] * sg) * cs[bj][1]; }
;                 else { v0 = v0 * cs[bj][0]; v1 = v1 * cs[bj][1]; }
;                 u32x4 w = {pack2(v0[0], v0[1]), pack2(v0[2], v0[3]), pack2(v1[0], v1[1]), pack2(v1[2], v1[3])};
;                 *(u32x4*)(outp + (size_t)lrow * ldo + bj * 128 + wc2 * 32 + c8) = w;
;               }
;             }
	v_lshlrev_b32_e32 v210, 16, v166
	v_and_b32_e32 v211, 0xffff0000, v166
	v_lshlrev_b32_e32 v212, 16, v167
	v_and_b32_e32 v213, 0xffff0000, v167
	v_lshlrev_b32_e32 v148, 16, v168
	v_and_b32_e32 v149, 0xffff0000, v168
	v_lshlrev_b32_e32 v150, 16, v169
	v_and_b32_e32 v151, 0xffff0000, v169
	s_add_u32 s34, s46, 0x40000
	s_addc_u32 s35, s47, 0
	global_load_dwordx4 v[166:169], v146, s[34:35]
	v_pk_fma_f32 v[210:211], v[194:195], 0.5, v[210:211] op_sel_hi:[1,0,1]
	v_pk_fma_f32 v[212:213], v[196:197], 0.5, v[212:213] op_sel_hi:[1,0,1]
	v_pk_fma_f32 v[148:149], v[198:199], 0.5, v[148:149] op_sel_hi:[1,0,1]
	v_pk_fma_f32 v[150:151], v[200:201], 0.5, v[150:151] op_sel_hi:[1,0,1]
	v_cvt_pk_bf16_f32 v194, v210, v211
	v_cvt_pk_bf16_f32 v195, v212, v213
	v_cvt_pk_bf16_f32 v196, v148, v149
	v_cvt_pk_bf16_f32 v197, v150, v151
	s_add_u32 s22, s46, 0x8000
	s_addc_u32 s23, s47, 0
	global_store_dwordx4 v146, v[194:197], s[22:23]
	v_pk_mul_f32 v[152:153], v[148:149], v[148:149]
	v_pk_mul_f32 v[156:157], v[150:151], v[150:151]
	v_pk_fma_f32 v[152:153], v[210:211], v[210:211], v[152:153]
	v_pk_fma_f32 v[156:157], v[212:213], v[212:213], v[156:157]
	v_add_f32_e32 v152, v152, v153
	v_add_f32_e32 v153, v156, v157
	v_add_f32_e32 v128, v152, v153
	ds_write2_b32 v144, v92, v88 offset1:16
	ds_write2_b32 v144, v93, v89 offset0:36 offset1:52
	ds_write2_b32 v144, v94, v90 offset0:72 offset1:88
	ds_write2_b32 v144, v95, v91 offset0:108 offset1:124
	ds_read_b128 v[194:197], v145
	ds_read_b128 v[198:201], v145 offset:16
	s_waitcnt lgkmcnt(6)
	v_add_f32_e32 v131, v131, v132
	s_add_u32 s94, s42, 0x0
	s_addc_u32 s95, s43, 0
	s_and_saveexec_b64 s[4:5], s[10:11]
	global_store_dword v147, v131, s[94:95]
	s_or_b64 exec, exec, s[4:5]
	s_waitcnt lgkmcnt(7)
	s_waitcnt vmcnt(9)
	v_lshlrev_b32_e32 v210, 16, v170
	v_and_b32_e32 v211, 0xffff0000, v170
	v_lshlrev_b32_e32 v212, 16, v171
	v_and_b32_e32 v213, 0xffff0000, v171
	v_lshlrev_b32_e32 v148, 16, v172
	v_and_b32_e32 v149, 0xffff0000, v172
	v_lshlrev_b32_e32 v150, 16, v173
	v_and_b32_e32 v151, 0xffff0000, v173
	global_load_dwordx4 v[170:173], v146, s[34:35] offset:256
	v_pk_fma_f32 v[210:211], v[202:203], 0.5, v[210:211] op_sel_hi:[1,0,1]
	v_pk_fma_f32 v[212:213], v[204:205], 0.5, v[212:213] op_sel_hi:[1,0,1]
	v_pk_fma_f32 v[148:149], v[206:207], 0.5, v[148:149] op_sel_hi:[1,0,1]
	v_pk_fma_f32 v[150:151], v[208:209], 0.5, v[150:151] op_sel_hi:[1,0,1]
	v_cvt_pk_bf16_f32 v202, v210, v211
	v_cvt_pk_bf16_f32 v203, v212, v213
	v_cvt_pk_bf16_f32 v204, v148, v149
	v_cvt_pk_bf16_f32 v205, v150, v151
	global_store_dwordx4 v146, v[202:205], s[22:23] offset:256
	v_pk_mul_f32 v[152:153], v[148:149], v[148:149]
	v_pk_mul_f32 v[156:157], v[150:151], v[150:151]
	v_pk_fma_f32 v[152:153], v[210:211], v[210:211], v[152:153]
	v_pk_fma_f32 v[156:157], v[212:213], v[212:213], v[156:157]
	v_add_f32_e32 v152, v152, v153
	v_add_f32_e32 v153, v156, v157
	v_add_f32_e32 v152, v152, v153
	v_add_f32_e32 v129, v128, v152
	ds_bpermute_b32 v130, v154, v129
	ds_write2_b32 v144, v84, v80 offset1:16
	ds_write2_b32 v144, v85, v81 offset0:36 offset1:52
	ds_write2_b32 v144, v86, v82 offset0:72 offset1:88
	ds_write2_b32 v144, v87, v83 offset0:108 offset1:124
	ds_read_b128 v[202:205], v145
	ds_read_b128 v[206:209], v145 offset:16
	s_waitcnt lgkmcnt(6)
	v_add_f32_e32 v131, v129, v130
	ds_bpermute_b32 v132, v155, v131
	s_waitcnt lgkmcnt(8)
	s_waitcnt vmcnt(10)
	v_lshlrev_b32_e32 v210, 16, v178
	v_and_b32_e32 v211, 0xffff0000, v178
	v_lshlrev_b32_e32 v212, 16, v179
	v_and_b32_e32 v213, 0xffff0000, v179
	v_lshlrev_b32_e32 v148, 16, v180
	v_and_b32_e32 v149, 0xffff0000, v180
	v_lshlrev_b32_e32 v150, 16, v181
	v_and_b32_e32 v151, 0xffff0000, v181
	s_add_u32 s34, s46, 0x48000
	s_addc_u32 s35, s47, 0
	global_load_dwordx4 v[178:181], v146, s[34:35]
	v_pk_fma_f32 v[210:211], v[194:195], 0.5, v[210:211] op_sel_hi:[1,0,1]
	v_pk_fma_f32 v[212:213], v[196:197], 0.5, v[212:213] op_sel_hi:[1,0,1]
	v_pk_fma_f32 v[148:149], v[198:199], 0.5, v[148:149] op_sel_hi:[1,0,1]
	v_pk_fma_f32 v[150:151], v[200:201], 0.5, v[150:151] op_sel_hi:[1,0,1]
	v_cvt_pk_bf16_f32 v194, v210, v211
	v_cvt_pk_bf16_f32 v195, v212, v213
	v_cvt_pk_bf16_f32 v196, v148, v149
	v_cvt_pk_bf16_f32 v197, v150, v151
	s_add_u32 s22, s46, 0x10000
	s_addc_u32 s23, s47, 0
	global_store_dwordx4 v146, v[194:197], s[22:23]
	v_pk_mul_f32 v[152:153], v[148:149], v[148:149]
	v_pk_mul_f32 v[156:157], v[150:151], v[150:151]
	v_pk_fma_f32 v[152:153], v[210:211], v[210:211], v[152:153]
	v_pk_fma_f32 v[156:157], v[212:213], v[212:213], v[156:157]
	v_add_f32_e32 v152, v152, v153
	v_add_f32_e32 v153, v156, v157
	v_add_f32_e32 v128, v152, v153
	ds_write2_b32 v144, v76, v72 offset1:16
	ds_write2_b32 v144, v77, v73 offset0:36 offset1:52
	ds_write2_b32 v144, v78, v74 offset0:72 offset1:88
	ds_write2_b32 v144, v79, v75 offset0:108 offset1:124
	ds_read_b128 v[194:197], v145
	ds_read_b128 v[198:201], v145 offset:16
	s_waitcnt lgkmcnt(6)
	v_add_f32_e32 v131, v131, v132
	s_add_u32 s94, s42, 0x400
	s_addc_u32 s95, s43, 0
	s_and_saveexec_b64 s[4:5], s[10:11]
	global_store_dword v147, v131, s[94:95]
	s_or_b64 exec, exec, s[4:5]
	s_waitcnt lgkmcnt(7)
	s_waitcnt vmcnt(12)
; template <int EPI>
; __device__ __forceinline__ void gemm_phase(const GemmDesc d, u16* shm, unsigned sx, unsigned srank, unsigned snloc) {
;     ...
;             for (int bj = 0; bj < 2; ++bj) {
; #pragma unroll
;               for (int n = 0; n < 2; ++n)
; #pragma unroll
;                 for (int j = 0; j < 4; ++j) stg[(fq2 * 4 + j) * 36 + n * 16 + fr2] = acc[ai][bj][m][n][j];
;               u32x4 xc = xi;
;               if constexpr (EPI == E_RESID) {
;                 const int rnd = (ai * 4 + m) * 2 + bj;
;                 if (rnd < 15) {
;                   const int rn = rnd + 1, an = rn >> 3, mn = (rn >> 1) & 3, bn = rn & 1;
;                   xi = *(const u32x4*)(d.xb + xbase + (size_t)(an * 128 + mn * 16) * DM + bn * 128);
;                 }
;               }
;               f32x4 v0 = *(const f32x4*)&stg[rl16 * 36 + c8], v1 = *(const f32x4*)&stg[rl16 * 36 + c8 + 4];
;               if constexpr (EPI == E_RESID) {
;                 const size_t idx = xbase + (size_t)(ai * 128 + m * 16) * DM + bj * 128;
;                 const f32x4 xo0 = {__uint_as_float(xc[0] << 16), __uint_as_float(xc[0] & 0xffff0000u), __uint_as_float(xc[1] << 16), __uint_as_float(xc[1] & 0xffff0000u)};
;                 const f32x4 xo1 = {__uint_as_float(xc[2] << 16), __uint_as_float(xc[2] & 0xffff0000u), __uint_as_float(xc[3] << 16), __uint_as_float(xc[3] & 0xffff0000u)};
;                 const f32x4 xn0 = xo0 + (v0 + cb[bj][0]) * cs[bj][0], xn1 = xo1 + (v1 + cb[bj][1]) * cs[bj][1];
;                 u32x4 w = {pack2(xn0[0], xn0[1]), pack2(xn0[2], xn0[3]), pack2(xn1[0], xn1[1]), pack2(xn1[2], xn1[3])};
;                 *(u32x4*)(d.xb + idx) = w;
;                 const f32x4 sq = xn0 * xn0 + xn1 * xn1;
;                 ps += (sq[0] + sq[1]) + (sq[2] + sq[3]);
;               } else {
;                 if constexpr (EPI == E_QKV) { const float r = lr[lrow]; v0 = v0 * r; v1 = v1 * r; }
;                 else if constexpr (EPI == E_SEQDFT) { const float sg = (rl16 & 1) ? -1.f : 1.f; v0 = (v0 + cb[bj][0] * sg) * cs[bj][0]; v1 = (v1 + cb[bj][1] * sg) * cs[bj][1]; }
;                 else { v0 = v0 * cs[bj][0]; v1 = v1 * cs[bj][1]; }
;                 u32x4 w = {pack2(v0[0], v0[1]), pack2(v0[2], v0[3]), pack2(v1[0], v1[1]), pack2(v1[2], v1[3])};
;                 *(u32x4*)(outp + (size_t)lrow * ldo + bj * 128 + wc2 * 32 + c8) = w;
;               }
;             }
	v_lshlrev_b32_e32 v210, 16, v190
	v_and_b32_e32 v211, 0xffff0000, v190
	v_lshlrev_b32_e32 v212, 16, v191
	v_and_b32_e32 v213, 0xffff0000, v191
	v_lshlrev_b32_e32 v148, 16, v192
	v_and_b32_e32 v149, 0xffff0000, v192
	v_lshlrev_b32_e32 v150, 16, v193
	v_and_b32_e32 v151, 0xffff0000, v193
	global_load_dwordx4 v[190:193], v146, s[34:35] offset:256
	v_pk_fma_f32 v[210:211], v[202:203], 0.5, v[210:211] op_sel_hi:[1,0,1]
	v_pk_fma_f32 v[212:213], v[204:205], 0.5, v[212:213] op_sel_hi:[1,0,1]
	v_pk_fma_f32 v[148:149], v[206:207], 0.5, v[148:149] op_sel_hi:[1,0,1]
	v_pk_fma_f32 v[150:151], v[208:209], 0.5, v[150:151] op_sel_hi:[1,0,1]
	v_cvt_pk_bf16_f32 v202, v210, v211
	v_cvt_pk_bf16_f32 v203, v212, v213
	v_cvt_pk_bf16_f32 v204, v148, v149
	v_cvt_pk_bf16_f32 v205, v150, v151
	global_store_dwordx4 v146, v[202:205], s[22:23] offset:256
	v_pk_mul_f32 v[152:153], v[148:149], v[148:149]
	v_pk_mul_f32 v[156:157], v[150:151], v[150:151]
	v_pk_fma_f32 v[152:153], v[210:211], v[210:211], v[152:153]
	v_pk_fma_f32 v[156:157], v[212:213], v[212:213], v[156:157]
	v_add_f32_e32 v152, v152, v153
	v_add_f32_e32 v153, v156, v157
	v_add_f32_e32 v152, v152, v153
	v_add_f32_e32 v129, v128, v152
	ds_bpermute_b32 v130, v154, v129
	ds_write2_b32 v144, v68, v64 offset1:16
	ds_write2_b32 v144, v69, v65 offset0:36 offset1:52
	ds_write2_b32 v144, v70, v66 offset0:72 offset1:88
	ds_write2_b32 v144, v71, v67 offset0:108 offset1:124
	ds_read_b128 v[202:205], v145
	ds_read_b128 v[206:209], v145 offset:16
	s_waitcnt lgkmcnt(6)
	v_add_f32_e32 v131, v129, v130
	ds_bpermute_b32 v132, v155, v131
	s_waitcnt lgkmcnt(8)
	s_waitcnt vmcnt(13)
	v_lshlrev_b32_e32 v210, 16, v158
	v_and_b32_e32 v211, 0xffff0000, v158
	v_lshlrev_b32_e32 v212, 16, v159
	v_and_b32_e32 v213, 0xffff0000, v159
	v_lshlrev_b32_e32 v148, 16, v160
	v_and_b32_e32 v149, 0xffff0000, v160
	v_lshlrev_b32_e32 v150, 16, v161
	v_and_b32_e32 v151, 0xffff0000, v161
	s_add_u32 s34, s46, 0x50000
	s_addc_u32 s35, s47, 0
	global_load_dwordx4 v[158:161], v146, s[34:35]
	v_pk_fma_f32 v[210:211], v[194:195], 0.5, v[210:211] op_sel_hi:[1,0,1]
	v_pk_fma_f32 v[212:213], v[196:197], 0.5, v[212:213] op_sel_hi:[1,0,1]
	v_pk_fma_f32 v[148:149], v[198:199], 0.5, v[148:149] op_sel_hi:[1,0,1]
	v_pk_fma_f32 v[150:151], v[200:201], 0.5, v[150:151] op_sel_hi:[1,0,1]
	v_cvt_pk_bf16_f32 v194, v210, v211
	v_cvt_pk_bf16_f32 v195, v212, v213
	v_cvt_pk_bf16_f32 v196, v148, v149
	v_cvt_pk_bf16_f32 v197, v150, v151
	s_add_u32 s22, s46, 0x18000
	s_addc_u32 s23, s47, 0
	global_store_dwordx4 v146, v[194:197], s[22:23]
	v_pk_mul_f32 v[152:153], v[148:149], v[148:149]
	v_pk_mul_f32 v[156:157], v[150:151], v[150:151]
	v_pk_fma_f32 v[152:153], v[210:211], v[210:211], v[152:153]
	v_pk_fma_f32 v[156:157], v[212:213], v[212:213], v[156:157]
	v_add_f32_e32 v152, v152, v153
	v_add_f32_e32 v153, v156, v157
	v_add_f32_e32 v128, v152, v153
	ds_write2_b32 v144, v60, v56 offset1:16
	ds_write2_b32 v144, v61, v57 offset0:36 offset1:52
	ds_write2_b32 v144, v62, v58 offset0:72 offset1:88
	ds_write2_b32 v144, v63, v59 offset0:108 offset1:124
	ds_read_b128 v[194:197], v145
	ds_read_b128 v[198:201], v145 offset:16
	s_waitcnt lgkmcnt(6)
	v_add_f32_e32 v131, v131, v132
	s_add_u32 s94, s42, 0x800
	s_addc_u32 s95, s43, 0
	s_and_saveexec_b64 s[4:5], s[10:11]
	global_store_dword v147, v131, s[94:95]
	s_or_b64 exec, exec, s[4:5]
	s_waitcnt lgkmcnt(7)
	s_waitcnt vmcnt(14)
	v_lshlrev_b32_e32 v210, 16, v162
	v_and_b32_e32 v211, 0xffff0000, v162
	v_lshlrev_b32_e32 v212, 16, v163
	v_and_b32_e32 v213, 0xffff0000, v163
	v_lshlrev_b32_e32 v148, 16, v164
	v_and_b32_e32 v149, 0xffff0000, v164
	v_lshlrev_b32_e32 v150, 16, v165
	v_and_b32_e32 v151, 0xffff0000, v165
	global_load_dwordx4 v[162:165], v146, s[34:35] offset:256
	v_pk_fma_f32 v[210:211], v[202:203], 0.5, v[210:211] op_sel_hi:[1,0,1]
	v_pk_fma_f32 v[212:213], v[204:205], 0.5, v[212:213] op_sel_hi:[1,0,1]
	v_pk_fma_f32 v[148:149], v[206:207], 0.5, v[148:149] op_sel_hi:[1,0,1]
	v_pk_fma_f32 v[150:151], v[208:209], 0.5, v[150:151] op_sel_hi:[1,0,1]
	v_cvt_pk_bf16_f32 v202, v210, v211
	v_cvt_pk_bf16_f32 v203, v212, v213
	v_cvt_pk_bf16_f32 v204, v148, v149
	v_cvt_pk_bf16_f32 v205, v150, v151
	global_store_dwordx4 v146, v[202:205], s[22:23] offset:256
	v_pk_mul_f32 v[152:153], v[148:149], v[148:149]
	v_pk_mul_f32 v[156:157], v[150:151], v[150:151]
	v_pk_fma_f32 v[152:153], v[210:211], v[210:211], v[152:153]
	v_pk_fma_f32 v[156:157], v[212:213], v[212:213], v[156:157]
	v_add_f32_e32 v152, v152, v153
	v_add_f32_e32 v153, v156, v157
	v_add_f32_e32 v152, v152, v153
	v_add_f32_e32 v129, v128, v152
	ds_bpermute_b32 v130, v154, v129
	ds_write2_b32 v144, v52, v48 offset1:16
	ds_write2_b32 v144, v53, v49 offset0:36 offset1:52
	ds_write2_b32 v144, v54, v50 offset0:72 offset1:88
	ds_write2_b32 v144, v55, v51 offset0:108 offset1:124
	ds_read_b128 v[202:205], v145
	ds_read_b128 v[206:209], v145 offset:16
	s_waitcnt lgkmcnt(6)
	v_add_f32_e32 v131, v129, v130
	ds_bpermute_b32 v132, v155, v131
	s_waitcnt lgkmcnt(8)
	s_waitcnt vmcnt(14)
; template <int EPI>
; __device__ __forceinline__ void gemm_phase(const GemmDesc d, u16* shm, unsigned sx, unsigned srank, unsigned snloc) {
;     ...
;             for (int bj = 0; bj < 2; ++bj) {
; #pragma unroll
;               for (int n = 0; n < 2; ++n)
; #pragma unroll
;                 for (int j = 0; j < 4; ++j) stg[(fq2 * 4 + j) * 36 + n * 16 + fr2] = acc[ai][bj][m][n][j];
;               u32x4 xc = xi;
;               if constexpr (EPI == E_RESID) {
;                 const int rnd = (ai * 4 + m) * 2 + bj;
;                 if (rnd < 15) {
;                   const int rn = rnd + 1, an = rn >> 3, mn = (rn >> 1) & 3, bn = rn & 1;
;                   xi = *(const u32x4*)(d.xb + xbase + (size_t)(an * 128 + mn * 16) * DM + bn * 128);
;                 }
;               }
;               f32x4 v0 = *(const f32x4*)&stg[rl16 * 36 + c8], v1 = *(const f32x4*)&stg[rl16 * 36 + c8 + 4];
;               if constexpr (EPI == E_RESID) {
;                 const size_t idx = xbase + (size_t)(ai * 128 + m * 16) * DM + bj * 128;
;                 const f32x4 xo0 = {__uint_as_float(xc[0] << 16), __uint_as_float(xc[0] & 0xffff0000u), __uint_as_float(xc[1] << 16), __uint_as_float(xc[1] & 0xffff0000u)};
;                 const f32x4 xo1 = {__uint_as_float(xc[2] << 16), __uint_as_float(xc[2] & 0xffff0000u), __uint_as_float(xc[3] << 16), __uint_as_float(xc[3] & 0xffff0000u)};
;                 const f32x4 xn0 = xo0 + (v0 + cb[bj][0]) * cs[bj][0], xn1 = xo1 + (v1 + cb[bj][1]) * cs[bj][1];
;                 u32x4 w = {pack2(xn0[0], xn0[1]), pack2(xn0[2], xn0[3]), pack2(xn1[0], xn1[1]), pack2(xn1[2], xn1[3])};
;                 *(u32x4*)(d.xb + idx) = w;
;                 const f32x4 sq = xn0 * xn0 + xn1 * xn1;
;                 ps += (sq[0] + sq[1]) + (sq[2] + sq[3]);
;               } else {
;                 if constexpr (EPI == E_QKV) { const float r = lr[lrow]; v0 = v0 * r; v1 = v1 * r; }
;                 else if constexpr (EPI == E_SEQDFT) { const float sg = (rl16 & 1) ? -1.f : 1.f; v0 = (v0 + cb[bj][0] * sg) * cs[bj][0]; v1 = (v1 + cb[bj][1] * sg) * cs[bj][1]; }
;                 else { v0 = v0 * cs[bj][0]; v1 = v1 * cs[bj][1]; }
;                 u32x4 w = {pack2(v0[0], v0[1]), pack2(v0[2], v0[3]), pack2(v1[0], v1[1]), pack2(v1[2], v1[3])};
;                 *(u32x4*)(outp + (size_t)lrow * ldo + bj * 128 + wc2 * 32 + c8) = w;
;               }
;             }
	v_lshlrev_b32_e32 v210, 16, v166
	v_and_b32_e32 v211, 0xffff0000, v166
	v_lshlrev_b32_e32 v212, 16, v167
	v_and_b32_e32 v213, 0xffff0000, v167
	v_lshlrev_b32_e32 v148, 16, v168
	v_and_b32_e32 v149, 0xffff0000, v168
	v_lshlrev_b32_e32 v150, 16, v169
	v_and_b32_e32 v151, 0xffff0000, v169
	s_add_u32 s34, s46, 0x58000
	s_addc_u32 s35, s47, 0
	global_load_dwordx4 v[166:169], v146, s[34:35]
	v_pk_fma_f32 v[210:211], v[194:195], 0.5, v[210:211] op_sel_hi:[1,0,1]
	v_pk_fma_f32 v[212:213], v[196:197], 0.5, v[212:213] op_sel_hi:[1,0,1]
	v_pk_fma_f32 v[148:149], v[198:199], 0.5, v[148:149] op_sel_hi:[1,0,1]
	v_pk_fma_f32 v[150:151], v[200:201], 0.5, v[150:151] op_sel_hi:[1,0,1]
	v_cvt_pk_bf16_f32 v194, v210, v211
	v_cvt_pk_bf16_f32 v195, v212, v213
	v_cvt_pk_bf16_f32 v196, v148, v149
	v_cvt_pk_bf16_f32 v197, v150, v151
	s_add_u32 s22, s46, 0x40000
	s_addc_u32 s23, s47, 0
	global_store_dwordx4 v146, v[194:197], s[22:23]
	v_pk_mul_f32 v[152:153], v[148:149], v[148:149]
	v_pk_mul_f32 v[156:157], v[150:151], v[150:151]
	v_pk_fma_f32 v[152:153], v[210:211], v[210:211], v[152:153]
	v_pk_fma_f32 v[156:157], v[212:213], v[212:213], v[156:157]
	v_add_f32_e32 v152, v152, v153
	v_add_f32_e32 v153, v156, v157
	v_add_f32_e32 v128, v152, v153
	ds_write2_b32 v144, v44, v40 offset1:16
	ds_write2_b32 v144, v45, v41 offset0:36 offset1:52
	ds_write2_b32 v144, v46, v42 offset0:72 offset1:88
	ds_write2_b32 v144, v47, v43 offset0:108 offset1:124
	ds_read_b128 v[194:197], v145
	ds_read_b128 v[198:201], v145 offset:16
	s_waitcnt lgkmcnt(6)
	v_add_f32_e32 v131, v131, v132
	s_add_u32 s94, s42, 0xc00
	s_addc_u32 s95, s43, 0
	s_and_saveexec_b64 s[4:5], s[10:11]
	global_store_dword v147, v131, s[94:95]
	s_or_b64 exec, exec, s[4:5]
	s_waitcnt lgkmcnt(7)
	s_waitcnt vmcnt(14)
	v_lshlrev_b32_e32 v210, 16, v170
	v_and_b32_e32 v211, 0xffff0000, v170
	v_lshlrev_b32_e32 v212, 16, v171
	v_and_b32_e32 v213, 0xffff0000, v171
	v_lshlrev_b32_e32 v148, 16, v172
	v_and_b32_e32 v149, 0xffff0000, v172
	v_lshlrev_b32_e32 v150, 16, v173
	v_and_b32_e32 v151, 0xffff0000, v173
	global_load_dwordx4 v[170:173], v146, s[34:35] offset:256
	v_pk_fma_f32 v[210:211], v[202:203], 0.5, v[210:211] op_sel_hi:[1,0,1]
	v_pk_fma_f32 v[212:213], v[204:205], 0.5, v[212:213] op_sel_hi:[1,0,1]
	v_pk_fma_f32 v[148:149], v[206:207], 0.5, v[148:149] op_sel_hi:[1,0,1]
	v_pk_fma_f32 v[150:151], v[208:209], 0.5, v[150:151] op_sel_hi:[1,0,1]
	v_cvt_pk_bf16_f32 v202, v210, v211
	v_cvt_pk_bf16_f32 v203, v212, v213
	v_cvt_pk_bf16_f32 v204, v148, v149
	v_cvt_pk_bf16_f32 v205, v150, v151
	global_store_dwordx4 v146, v[202:205], s[22:23] offset:256
	v_pk_mul_f32 v[152:153], v[148:149], v[148:149]
	v_pk_mul_f32 v[156:157], v[150:151], v[150:151]
	v_pk_fma_f32 v[152:153], v[210:211], v[210:211], v[152:153]
	v_pk_fma_f32 v[156:157], v[212:213], v[212:213], v[156:157]
	v_add_f32_e32 v152, v152, v153
	v_add_f32_e32 v153, v156, v157
	v_add_f32_e32 v152, v152, v153
	v_add_f32_e32 v129, v128, v152
	ds_bpermute_b32 v130, v154, v129
	ds_write2_b32 v144, v36, v32 offset1:16
	ds_write2_b32 v144, v37, v33 offset0:36 offset1:52
	ds_write2_b32 v144, v38, v34 offset0:72 offset1:88
	ds_write2_b32 v144, v39, v35 offset0:108 offset1:124
	ds_read_b128 v[202:205], v145
	ds_read_b128 v[206:209], v145 offset:16
	s_waitcnt lgkmcnt(6)
	v_add_f32_e32 v131, v129, v130
	ds_bpermute_b32 v132, v155, v131
	s_waitcnt lgkmcnt(8)
	s_waitcnt vmcnt(14)
	v_lshlrev_b32_e32 v210, 16, v178
	v_and_b32_e32 v211, 0xffff0000, v178
	v_lshlrev_b32_e32 v212, 16, v179
	v_and_b32_e32 v213, 0xffff0000, v179
	v_lshlrev_b32_e32 v148, 16, v180
	v_and_b32_e32 v149, 0xffff0000, v180
	v_lshlrev_b32_e32 v150, 16, v181
	v_and_b32_e32 v151, 0xffff0000, v181
	v_pk_fma_f32 v[210:211], v[194:195], 0.5, v[210:211] op_sel_hi:[1,0,1]
	v_pk_fma_f32 v[212:213], v[196:197], 0.5, v[212:213] op_sel_hi:[1,0,1]
	v_pk_fma_f32 v[148:149], v[198:199], 0.5, v[148:149] op_sel_hi:[1,0,1]
	v_pk_fma_f32 v[150:151], v[200:201], 0.5, v[150:151] op_sel_hi:[1,0,1]
	v_cvt_pk_bf16_f32 v194, v210, v211
	v_cvt_pk_bf16_f32 v195, v212, v213
	v_cvt_pk_bf16_f32 v196, v148, v149
	v_cvt_pk_bf16_f32 v197, v150, v151
	s_add_u32 s22, s46, 0x48000
	s_addc_u32 s23, s47, 0
	global_store_dwordx4 v146, v[194:197], s[22:23]
	v_pk_mul_f32 v[152:153], v[148:149], v[148:149]
	v_pk_mul_f32 v[156:157], v[150:151], v[150:151]
	v_pk_fma_f32 v[152:153], v[210:211], v[210:211], v[152:153]
	v_pk_fma_f32 v[156:157], v[212:213], v[212:213], v[156:157]
	v_add_f32_e32 v152, v152, v153
	v_add_f32_e32 v153, v156, v157
	v_add_f32_e32 v128, v152, v153
	ds_write2_b32 v144, v28, v24 offset1:16
	ds_write2_b32 v144, v29, v25 offset0:36 offset1:52
	ds_write2_b32 v144, v30, v26 offset0:72 offset1:88
	ds_write2_b32 v144, v31, v27 offset0:108 offset1:124
	ds_read_b128 v[194:197], v145
	ds_read_b128 v[198:201], v145 offset:16
	s_waitcnt lgkmcnt(6)
	v_add_f32_e32 v131, v131, v132
	s_add_u32 s94, s42, 0x2000
	s_addc_u32 s95, s43, 0
	s_and_saveexec_b64 s[4:5], s[10:11]
	global_store_dword v147, v131, s[94:95]
	s_or_b64 exec, exec, s[4:5]
	s_waitcnt lgkmcnt(7)
	s_waitcnt vmcnt(13)
; template <int EPI>
; __device__ __forceinline__ void gemm_phase(const GemmDesc d, u16* shm, unsigned sx, unsigned srank, unsigned snloc) {
;     ...
;             for (int bj = 0; bj < 2; ++bj) {
; #pragma unroll
;               for (int n = 0; n < 2; ++n)
; #pragma unroll
;                 for (int j = 0; j < 4; ++j) stg[(fq2 * 4 + j) * 36 + n * 16 + fr2] = acc[ai][bj][m][n][j];
;               u32x4 xc = xi;
;               if constexpr (EPI == E_RESID) {
;                 const int rnd = (ai * 4 + m) * 2 + bj;
;                 if (rnd < 15) {
;                   const int rn = rnd + 1, an = rn >> 3, mn = (rn >> 1) & 3, bn = rn & 1;
;                   xi = *(const u32x4*)(d.xb + xbase + (size_t)(an * 128 + mn * 16) * DM + bn * 128);
;                 }
;               }
;               f32x4 v0 = *(const f32x4*)&stg[rl16 * 36 + c8], v1 = *(const f32x4*)&stg[rl16 * 36 + c8 + 4];
;               if constexpr (EPI == E_RESID) {
;                 const size_t idx = xbase + (size_t)(ai * 128 + m * 16) * DM + bj * 128;
;                 const f32x4 xo0 = {__uint_as_float(xc[0] << 16), __uint_as_float(xc[0] & 0xffff0000u), __uint_as_float(xc[1] << 16), __uint_as_float(xc[1] & 0xffff0000u)};
;                 const f32x4 xo1 = {__uint_as_float(xc[2] << 16), __uint_as_float(xc[2] & 0xffff0000u), __uint_as_float(xc[3] << 16), __uint_as_float(xc[3] & 0xffff0000u)};
;                 const f32x4 xn0 = xo0 + (v0 + cb[bj][0]) * cs[bj][0], xn1 = xo1 + (v1 + cb[bj][1]) * cs[bj][1];
;                 u32x4 w = {pack2(xn0[0], xn0[1]), pack2(xn0[2], xn0[3]), pack2(xn1[0], xn1[1]), pack2(xn1[2], xn1[3])};
;                 *(u32x4*)(d.xb + idx) = w;
;                 const f32x4 sq = xn0 * xn0 + xn1 * xn1;
;                 ps += (sq[0] + sq[1]) + (sq[2] + sq[3]);
;               } else {
;                 if constexpr (EPI == E_QKV) { const float r = lr[lrow]; v0 = v0 * r; v1 = v1 * r; }
;                 else if constexpr (EPI == E_SEQDFT) { const float sg = (rl16 & 1) ? -1.f : 1.f; v0 = (v0 + cb[bj][0] * sg) * cs[bj][0]; v1 = (v1 + cb[bj][1] * sg) * cs[bj][1]; }
;                 else { v0 = v0 * cs[bj][0]; v1 = v1 * cs[bj][1]; }
;                 u32x4 w = {pack2(v0[0], v0[1]), pack2(v0[2], v0[3]), pack2(v1[0], v1[1]), pack2(v1[2], v1[3])};
;                 *(u32x4*)(outp + (size_t)lrow * ldo + bj * 128 + wc2 * 32 + c8) = w;
;               }
;             }
	v_lshlrev_b32_e32 v210, 16, v190
	v_and_b32_e32 v211, 0xffff0000, v190
	v_lshlrev_b32_e32 v212, 16, v191
	v_and_b32_e32 v213, 0xffff0000, v191
	v_lshlrev_b32_e32 v148, 16, v192
	v_and_b32_e32 v149, 0xffff0000, v192
	v_lshlrev_b32_e32 v150, 16, v193
	v_and_b32_e32 v151, 0xffff0000, v193
	v_pk_fma_f32 v[210:211], v[202:203], 0.5, v[210:211] op_sel_hi:[1,0,1]
	v_pk_fma_f32 v[212:213], v[204:205], 0.5, v[212:213] op_sel_hi:[1,0,1]
	v_pk_fma_f32 v[148:149], v[206:207], 0.5, v[148:149] op_sel_hi:[1,0,1]
	v_pk_fma_f32 v[150:151], v[208:209], 0.5, v[150:151] op_sel_hi:[1,0,1]
	v_cvt_pk_bf16_f32 v202, v210, v211
	v_cvt_pk_bf16_f32 v203, v212, v213
	v_cvt_pk_bf16_f32 v204, v148, v149
	v_cvt_pk_bf16_f32 v205, v150, v151
	global_store_dwordx4 v146, v[202:205], s[22:23] offset:256
	v_pk_mul_f32 v[152:153], v[148:149], v[148:149]
	v_pk_mul_f32 v[156:157], v[150:151], v[150:151]
	v_pk_fma_f32 v[152:153], v[210:211], v[210:211], v[152:153]
	v_pk_fma_f32 v[156:157], v[212:213], v[212:213], v[156:157]
	v_add_f32_e32 v152, v152, v153
	v_add_f32_e32 v153, v156, v157
	v_add_f32_e32 v152, v152, v153
	v_add_f32_e32 v129, v128, v152
	ds_bpermute_b32 v130, v154, v129
	ds_write2_b32 v144, v20, v16 offset1:16
	ds_write2_b32 v144, v21, v17 offset0:36 offset1:52
	ds_write2_b32 v144, v22, v18 offset0:72 offset1:88
	ds_write2_b32 v144, v23, v19 offset0:108 offset1:124
	ds_read_b128 v[202:205], v145
	ds_read_b128 v[206:209], v145 offset:16
	s_waitcnt lgkmcnt(6)
	v_add_f32_e32 v131, v129, v130
	ds_bpermute_b32 v132, v155, v131
	s_waitcnt lgkmcnt(8)
	s_waitcnt vmcnt(12)
	v_lshlrev_b32_e32 v210, 16, v158
	v_and_b32_e32 v211, 0xffff0000, v158
	v_lshlrev_b32_e32 v212, 16, v159
	v_and_b32_e32 v213, 0xffff0000, v159
	v_lshlrev_b32_e32 v148, 16, v160
	v_and_b32_e32 v149, 0xffff0000, v160
	v_lshlrev_b32_e32 v150, 16, v161
	v_and_b32_e32 v151, 0xffff0000, v161
	v_pk_fma_f32 v[210:211], v[194:195], 0.5, v[210:211] op_sel_hi:[1,0,1]
	v_pk_fma_f32 v[212:213], v[196:197], 0.5, v[212:213] op_sel_hi:[1,0,1]
	v_pk_fma_f32 v[148:149], v[198:199], 0.5, v[148:149] op_sel_hi:[1,0,1]
	v_pk_fma_f32 v[150:151], v[200:201], 0.5, v[150:151] op_sel_hi:[1,0,1]
	v_cvt_pk_bf16_f32 v194, v210, v211
	v_cvt_pk_bf16_f32 v195, v212, v213
	v_cvt_pk_bf16_f32 v196, v148, v149
	v_cvt_pk_bf16_f32 v197, v150, v151
	s_add_u32 s22, s46, 0x50000
	s_addc_u32 s23, s47, 0
	global_store_dwordx4 v146, v[194:197], s[22:23]
	v_pk_mul_f32 v[152:153], v[148:149], v[148:149]
	v_pk_mul_f32 v[156:157], v[150:151], v[150:151]
	v_pk_fma_f32 v[152:153], v[210:211], v[210:211], v[152:153]
	v_pk_fma_f32 v[156:157], v[212:213], v[212:213], v[156:157]
	v_add_f32_e32 v152, v152, v153
	v_add_f32_e32 v153, v156, v157
	v_add_f32_e32 v128, v152, v153
	ds_write2_b32 v144, v12, v8 offset1:16
	ds_write2_b32 v144, v13, v9 offset0:36 offset1:52
	ds_write2_b32 v144, v14, v10 offset0:72 offset1:88
	ds_write2_b32 v144, v15, v11 offset0:108 offset1:124
	ds_read_b128 v[194:197], v145
	ds_read_b128 v[198:201], v145 offset:16
	s_waitcnt lgkmcnt(6)
	v_add_f32_e32 v131, v131, v132
	s_add_u32 s94, s42, 0x2400
	s_addc_u32 s95, s43, 0
	s_and_saveexec_b64 s[4:5], s[10:11]
	global_store_dword v147, v131, s[94:95]
	s_or_b64 exec, exec, s[4:5]
	s_waitcnt lgkmcnt(7)
	s_waitcnt vmcnt(11)
; template <int EPI>
; __device__ __forceinline__ void gemm_phase(const GemmDesc d, u16* shm, unsigned sx, unsigned srank, unsigned snloc) {
;     ...
;             for (int bj = 0; bj < 2; ++bj) {
; #pragma unroll
;               for (int n = 0; n < 2; ++n)
; #pragma unroll
;                 for (int j = 0; j < 4; ++j) stg[(fq2 * 4 + j) * 36 + n * 16 + fr2] = acc[ai][bj][m][n][j];
;               u32x4 xc = xi;
;               if constexpr (EPI == E_RESID) {
;                 const int rnd = (ai * 4 + m) * 2 + bj;
;                 if (rnd < 15) {
;                   const int rn = rnd + 1, an = rn >> 3, mn = (rn >> 1) & 3, bn = rn & 1;
;                   xi = *(const u32x4*)(d.xb + xbase + (size_t)(an * 128 + mn * 16) * DM + bn * 128);
;                 }
;               }
;               f32x4 v0 = *(const f32x4*)&stg[rl16 * 36 + c8], v1 = *(const f32x4*)&stg[rl16 * 36 + c8 + 4];
;               if constexpr (EPI == E_RESID) {
;                 const size_t idx = xbase + (size_t)(ai * 128 + m * 16) * DM + bj * 128;
;                 const f32x4 xo0 = {__uint_as_float(xc[0] << 16), __uint_as_float(xc[0] & 0xffff0000u), __uint_as_float(xc[1] << 16), __uint_as_float(xc[1] & 0xffff0000u)};
;                 const f32x4 xo1 = {__uint_as_float(xc[2] << 16), __uint_as_float(xc[2] & 0xffff0000u), __uint_as_float(xc[3] << 16), __uint_as_float(xc[3] & 0xffff0000u)};
;                 const f32x4 xn0 = xo0 + (v0 + cb[bj][0]) * cs[bj][0], xn1 = xo1 + (v1 + cb[bj][1]) * cs[bj][1];
;                 u32x4 w = {pack2(xn0[0], xn0[1]), pack2(xn0[2], xn0[3]), pack2(xn1[0], xn1[1]), pack2(xn1[2], xn1[3])};
;                 *(u32x4*)(d.xb + idx) = w;
;                 const f32x4 sq = xn0 * xn0 + xn1 * xn1;
;                 ps += (sq[0] + sq[1]) + (sq[2] + sq[3]);
;               } else {
;                 if constexpr (EPI == E_QKV) { const float r = lr[lrow]; v0 = v0 * r; v1 = v1 * r; }
;                 else if constexpr (EPI == E_SEQDFT) { const float sg = (rl16 & 1) ? -1.f : 1.f; v0 = (v0 + cb[bj][0] * sg) * cs[bj][0]; v1 = (v1 + cb[bj][1] * sg) * cs[bj][1]; }
;                 else { v0 = v0 * cs[bj][0]; v1 = v1 * cs[bj][1]; }
;                 u32x4 w = {pack2(v0[0], v0[1]), pack2(v0[2], v0[3]), pack2(v1[0], v1[1]), pack2(v1[2], v1[3])};
;                 *(u32x4*)(outp + (size_t)lrow * ldo + bj * 128 + wc2 * 32 + c8) = w;
;               }
;             }
	v_lshlrev_b32_e32 v210, 16, v162
	v_and_b32_e32 v211, 0xffff0000, v162
	v_lshlrev_b32_e32 v212, 16, v163
	v_and_b32_e32 v213, 0xffff0000, v163
	v_lshlrev_b32_e32 v148, 16, v164
	v_and_b32_e32 v149, 0xffff0000, v164
	v_lshlrev_b32_e32 v150, 16, v165
	v_and_b32_e32 v151, 0xffff0000, v165
	v_pk_fma_f32 v[210:211], v[202:203], 0.5, v[210:211] op_sel_hi:[1,0,1]
	v_pk_fma_f32 v[212:213], v[204:205], 0.5, v[212:213] op_sel_hi:[1,0,1]
	v_pk_fma_f32 v[148:149], v[206:207], 0.5, v[148:149] op_sel_hi:[1,0,1]
	v_pk_fma_f32 v[150:151], v[208:209], 0.5, v[150:151] op_sel_hi:[1,0,1]
	v_cvt_pk_bf16_f32 v202, v210, v211
	v_cvt_pk_bf16_f32 v203, v212, v213
	v_cvt_pk_bf16_f32 v204, v148, v149
	v_cvt_pk_bf16_f32 v205, v150, v151
	global_store_dwordx4 v146, v[202:205], s[22:23] offset:256
	v_pk_mul_f32 v[152:153], v[148:149], v[148:149]
	v_pk_mul_f32 v[156:157], v[150:151], v[150:151]
	v_pk_fma_f32 v[152:153], v[210:211], v[210:211], v[152:153]
	v_pk_fma_f32 v[156:157], v[212:213], v[212:213], v[156:157]
	v_add_f32_e32 v152, v152, v153
	v_add_f32_e32 v153, v156, v157
	v_add_f32_e32 v152, v152, v153
	v_add_f32_e32 v129, v128, v152
	ds_bpermute_b32 v130, v154, v129
	ds_write2_b32 v144, v4, v0 offset1:16
	ds_write2_b32 v144, v5, v1 offset0:36 offset1:52
	ds_write2_b32 v144, v6, v2 offset0:72 offset1:88
	ds_write2_b32 v144, v7, v3 offset0:108 offset1:124
	ds_read_b128 v[202:205], v145
	ds_read_b128 v[206:209], v145 offset:16
	s_waitcnt lgkmcnt(6)
	v_add_f32_e32 v131, v129, v130
	ds_bpermute_b32 v132, v155, v131
	s_waitcnt lgkmcnt(8)
	s_waitcnt vmcnt(10)
	v_lshlrev_b32_e32 v210, 16, v166
	v_and_b32_e32 v211, 0xffff0000, v166
	v_lshlrev_b32_e32 v212, 16, v167
	v_and_b32_e32 v213, 0xffff0000, v167
	v_lshlrev_b32_e32 v148, 16, v168
	v_and_b32_e32 v149, 0xffff0000, v168
	v_lshlrev_b32_e32 v150, 16, v169
	v_and_b32_e32 v151, 0xffff0000, v169
	v_pk_fma_f32 v[210:211], v[194:195], 0.5, v[210:211] op_sel_hi:[1,0,1]
	v_pk_fma_f32 v[212:213], v[196:197], 0.5, v[212:213] op_sel_hi:[1,0,1]
	v_pk_fma_f32 v[148:149], v[198:199], 0.5, v[148:149] op_sel_hi:[1,0,1]
	v_pk_fma_f32 v[150:151], v[200:201], 0.5, v[150:151] op_sel_hi:[1,0,1]
	v_cvt_pk_bf16_f32 v194, v210, v211
	v_cvt_pk_bf16_f32 v195, v212, v213
	v_cvt_pk_bf16_f32 v196, v148, v149
	v_cvt_pk_bf16_f32 v197, v150, v151
	s_add_u32 s22, s46, 0x58000
	s_addc_u32 s23, s47, 0
	global_store_dwordx4 v146, v[194:197], s[22:23]
	v_pk_mul_f32 v[152:153], v[148:149], v[148:149]
	v_pk_mul_f32 v[156:157], v[150:151], v[150:151]
	v_pk_fma_f32 v[152:153], v[210:211], v[210:211], v[152:153]
	v_pk_fma_f32 v[156:157], v[212:213], v[212:213], v[156:157]
	v_add_f32_e32 v152, v152, v153
	v_add_f32_e32 v153, v156, v157
	v_add_f32_e32 v128, v152, v153
	s_waitcnt lgkmcnt(0)
	v_add_f32_e32 v131, v131, v132
	s_add_u32 s94, s42, 0x2800
	s_addc_u32 s95, s43, 0
	s_and_saveexec_b64 s[4:5], s[10:11]
	global_store_dword v147, v131, s[94:95]
	s_or_b64 exec, exec, s[4:5]
	s_waitcnt lgkmcnt(1)
	s_waitcnt vmcnt(9)
	v_lshlrev_b32_e32 v210, 16, v170
	v_and_b32_e32 v211, 0xffff0000, v170
	v_lshlrev_b32_e32 v212, 16, v171
	v_and_b32_e32 v213, 0xffff0000, v171
	v_lshlrev_b32_e32 v148, 16, v172
	v_and_b32_e32 v149, 0xffff0000, v172
	v_lshlrev_b32_e32 v150, 16, v173
	v_and_b32_e32 v151, 0xffff0000, v173
	v_pk_fma_f32 v[210:211], v[202:203], 0.5, v[210:211] op_sel_hi:[1,0,1]
	v_pk_fma_f32 v[212:213], v[204:205], 0.5, v[212:213] op_sel_hi:[1,0,1]
	v_pk_fma_f32 v[148:149], v[206:207], 0.5, v[148:149] op_sel_hi:[1,0,1]
	v_pk_fma_f32 v[150:151], v[208:209], 0.5, v[150:151] op_sel_hi:[1,0,1]
	v_cvt_pk_bf16_f32 v202, v210, v211
	v_cvt_pk_bf16_f32 v203, v212, v213
	v_cvt_pk_bf16_f32 v204, v148, v149
	v_cvt_pk_bf16_f32 v205, v150, v151
	global_store_dwordx4 v146, v[202:205], s[22:23] offset:256
	v_pk_mul_f32 v[152:153], v[148:149], v[148:149]
	v_pk_mul_f32 v[156:157], v[150:151], v[150:151]
	v_pk_fma_f32 v[152:153], v[210:211], v[210:211], v[152:153]
	v_pk_fma_f32 v[156:157], v[212:213], v[212:213], v[156:157]
	v_add_f32_e32 v152, v152, v153
	v_add_f32_e32 v153, v156, v157
	v_add_f32_e32 v152, v152, v153
	v_add_f32_e32 v129, v128, v152
	ds_bpermute_b32 v130, v154, v129
	s_waitcnt lgkmcnt(0)
	v_add_f32_e32 v131, v129, v130
	ds_bpermute_b32 v132, v155, v131
	s_waitcnt lgkmcnt(0)
	v_add_f32_e32 v131, v131, v132
	s_add_u32 s94, s42, 0x2c00
	s_addc_u32 s95, s43, 0
	s_and_saveexec_b64 s[4:5], s[10:11]
	global_store_dword v147, v131, s[94:95]
	s_or_b64 exec, exec, s[4:5]
	s_mov_b32 s31, 0x800000
	s_movk_i32 s28, 0x1000
	s_mov_b64 s[4:5], 0
